# phase1 K-loop: compiler-inserted vmcnt(0) at loop head hoisted to preheader
# speedup vs baseline: 1.0005x; 1.0005x over previous
.LBB0_174:
	s_xor_b64 s[10:11], s[8:9], -1
	s_mov_b32 s24, s29
	v_writelane_b32 v252, s10, 49
	s_ashr_i32 s25, s29, 31
	v_readlane_b32 s56, v253, 34
	v_writelane_b32 v252, s11, 50
	s_lshl_b64 s[10:11], s[24:25], 19
	v_readlane_b32 s62, v253, 40
	v_readlane_b32 s63, v253, 41
	s_add_u32 s20, s62, s10
	s_addc_u32 s21, s63, s11
	s_and_b64 s[10:11], s[8:9], exec
	s_mov_b32 s16, s30
	s_cselect_b32 s10, s21, s5
	s_cselect_b32 s11, s20, s4
	s_ashr_i32 s17, s30, 31
	v_readlane_b32 s64, v253, 42
	s_lshl_b64 s[30:31], s[16:17], 19
	v_readlane_b32 s65, v253, 43
	s_add_u32 s54, s64, s30
	s_addc_u32 s55, s65, s31
	s_and_b64 s[8:9], s[8:9], exec
	s_cselect_b32 s25, s55, s7
	s_cselect_b32 s29, s54, s6
	s_add_u32 s4, s4, 0x40080
	s_addc_u32 s5, s5, 0
	s_add_u32 s30, s6, 0x100
	v_mov_b32_e32 v0, 0
	s_addc_u32 s31, s7, 0
	s_mov_b32 s34, -2
	v_mov_b32_e32 v1, v0
	v_mov_b32_e32 v2, v0
	v_mov_b32_e32 v3, v0
	v_mov_b32_e32 v4, v0
	v_mov_b32_e32 v5, v0
	v_mov_b32_e32 v6, v0
	v_mov_b32_e32 v7, v0
	v_mov_b32_e32 v32, v0
	v_mov_b32_e32 v33, v0
	v_mov_b32_e32 v34, v0
	v_mov_b32_e32 v35, v0
	v_mov_b32_e32 v36, v0
	v_mov_b32_e32 v37, v0
	v_mov_b32_e32 v38, v0
	v_mov_b32_e32 v39, v0
	v_mov_b32_e32 v64, v0
	v_mov_b32_e32 v65, v0
	v_mov_b32_e32 v66, v0
	v_mov_b32_e32 v67, v0
	v_mov_b32_e32 v68, v0
	v_mov_b32_e32 v69, v0
	v_mov_b32_e32 v70, v0
	v_mov_b32_e32 v71, v0
	v_mov_b32_e32 v80, v0
	s_waitcnt lgkmcnt(0)
	v_mov_b32_e32 v81, v0
	v_mov_b32_e32 v82, v0
	v_mov_b32_e32 v83, v0
	v_mov_b32_e32 v84, v0
	v_mov_b32_e32 v85, v0
	v_mov_b32_e32 v86, v0
	v_mov_b32_e32 v87, v0
	v_mov_b32_e32 v8, v0
	v_mov_b32_e32 v9, v0
	v_mov_b32_e32 v10, v0
	v_mov_b32_e32 v11, v0
	v_mov_b32_e32 v12, v0
	v_mov_b32_e32 v13, v0
	v_mov_b32_e32 v14, v0
	v_mov_b32_e32 v15, v0
	v_mov_b32_e32 v56, v0
	v_mov_b32_e32 v57, v0
	v_mov_b32_e32 v58, v0
	v_mov_b32_e32 v59, v0
	v_mov_b32_e32 v60, v0
	v_mov_b32_e32 v61, v0
	v_mov_b32_e32 v62, v0
	v_mov_b32_e32 v63, v0
	v_mov_b32_e32 v72, v0
	v_mov_b32_e32 v73, v0
	v_mov_b32_e32 v74, v0
	v_mov_b32_e32 v75, v0
	v_mov_b32_e32 v76, v0
	v_mov_b32_e32 v77, v0
	v_mov_b32_e32 v78, v0
	v_mov_b32_e32 v79, v0
	v_mov_b32_e32 v88, v0
	v_mov_b32_e32 v89, v0
	v_mov_b32_e32 v90, v0
	v_mov_b32_e32 v91, v0
	v_mov_b32_e32 v92, v0
	v_mov_b32_e32 v93, v0
	v_mov_b32_e32 v94, v0
	v_mov_b32_e32 v95, v0
	v_mov_b32_e32 v96, v0
	v_mov_b32_e32 v97, v0
	v_mov_b32_e32 v98, v0
	v_mov_b32_e32 v99, v0
	v_mov_b32_e32 v100, v0
	v_mov_b32_e32 v101, v0
	v_mov_b32_e32 v102, v0
	v_mov_b32_e32 v103, v0
	v_mov_b32_e32 v112, v0
	v_mov_b32_e32 v113, v0
	v_mov_b32_e32 v114, v0
	v_mov_b32_e32 v115, v0
	v_mov_b32_e32 v116, v0
	v_mov_b32_e32 v117, v0
	v_mov_b32_e32 v118, v0
	v_mov_b32_e32 v119, v0
	v_mov_b32_e32 v128, v0
	v_mov_b32_e32 v129, v0
	v_mov_b32_e32 v130, v0
	v_mov_b32_e32 v131, v0
	v_mov_b32_e32 v132, v0
	v_mov_b32_e32 v133, v0
	v_mov_b32_e32 v134, v0
	v_mov_b32_e32 v135, v0
	v_mov_b32_e32 v144, v0
	v_mov_b32_e32 v145, v0
	v_mov_b32_e32 v146, v0
	v_mov_b32_e32 v147, v0
	v_mov_b32_e32 v148, v0
	v_mov_b32_e32 v149, v0
	v_mov_b32_e32 v150, v0
	v_mov_b32_e32 v151, v0
	v_mov_b32_e32 v104, v0
	v_mov_b32_e32 v105, v0
	v_mov_b32_e32 v106, v0
	v_mov_b32_e32 v107, v0
	v_mov_b32_e32 v108, v0
	v_mov_b32_e32 v109, v0
	v_mov_b32_e32 v110, v0
	v_mov_b32_e32 v111, v0
	v_mov_b32_e32 v120, v0
	v_mov_b32_e32 v121, v0
	v_mov_b32_e32 v122, v0
	v_mov_b32_e32 v123, v0
	v_mov_b32_e32 v124, v0
	v_mov_b32_e32 v125, v0
	v_mov_b32_e32 v126, v0
	v_mov_b32_e32 v127, v0
	v_mov_b32_e32 v136, v0
	v_mov_b32_e32 v137, v0
	v_mov_b32_e32 v138, v0
	v_mov_b32_e32 v139, v0
	v_mov_b32_e32 v140, v0
	v_mov_b32_e32 v141, v0
	v_mov_b32_e32 v142, v0
	v_mov_b32_e32 v143, v0
	v_mov_b32_e32 v152, v0
	v_mov_b32_e32 v153, v0
	v_mov_b32_e32 v154, v0
	v_mov_b32_e32 v155, v0
	v_mov_b32_e32 v156, v0
	v_mov_b32_e32 v157, v0
	v_mov_b32_e32 v158, v0
	v_mov_b32_e32 v159, v0
	v_readlane_b32 s57, v253, 35
	v_readlane_b32 s58, v253, 36
	v_readlane_b32 s59, v253, 37
	v_readlane_b32 s60, v253, 38
	v_readlane_b32 s61, v253, 39
	v_readlane_b32 s66, v253, 44
	v_readlane_b32 s67, v253, 45
	v_readlane_b32 s68, v253, 46
	v_readlane_b32 s69, v253, 47
	v_readlane_b32 s70, v253, 48
	v_readlane_b32 s71, v253, 49
	s_waitcnt vmcnt(0)
.LBB0_175:
	ds_read_b128 v[16:19], v233
	ds_read_b128 v[20:23], v233 offset:1024
	ds_read_b128 v[24:27], v233 offset:2048
	ds_read_b128 v[28:31], v233 offset:3072
	s_add_u32 s6, s4, 0xfffc0080
	s_addc_u32 s7, s5, -1
	s_cmp_eq_u32 s34, 12
	s_cselect_b32 s9, s10, s7
	s_cselect_b32 s8, s11, s6
	s_cselect_b32 s7, s25, s31
	s_cselect_b32 s6, s29, s30
	v_lshl_add_u64 v[202:203], s[4:5], 0, v[182:183]
	s_add_i32 m0, s92, 0xc000
	ds_read_b128 v[40:43], v234
	ds_read_b128 v[44:47], v234 offset:1024
	ds_read_b128 v[48:51], v234 offset:2048
	ds_read_b128 v[52:55], v234 offset:3072
	ds_read_b128 v[186:189], v234 offset:4096
	ds_read_b128 v[190:193], v234 offset:5120
	ds_read_b128 v[194:197], v234 offset:6144
	ds_read_b128 v[198:201], v234 offset:7168
	global_load_lds_dwordx4 v[202:203], off
	v_lshl_add_u64 v[202:203], s[4:5], 0, v[184:185]
	s_add_i32 m0, s92, 0xe000
	s_nop 0
	global_load_lds_dwordx4 v[202:203], off
	s_waitcnt lgkmcnt(8)
	s_barrier
	s_waitcnt lgkmcnt(0)
	s_setprio 1
	s_waitcnt lgkmcnt(0)
	v_mfma_f32_16x16x32_bf16 v[156:159], v[16:19], v[40:43], v[156:159]
	v_mfma_f32_16x16x32_bf16 v[152:155], v[24:27], v[40:43], v[152:155]
	v_mfma_f32_16x16x32_bf16 v[140:143], v[16:19], v[48:51], v[140:143]
	v_mfma_f32_16x16x32_bf16 v[136:139], v[24:27], v[48:51], v[136:139]
	v_mfma_f32_16x16x32_bf16 v[124:127], v[16:19], v[186:189], v[124:127]
	v_mfma_f32_16x16x32_bf16 v[120:123], v[24:27], v[186:189], v[120:123]
	v_mfma_f32_16x16x32_bf16 v[108:111], v[16:19], v[194:197], v[108:111]
	v_mfma_f32_16x16x32_bf16 v[104:107], v[24:27], v[194:197], v[104:107]
	v_mfma_f32_16x16x32_bf16 v[156:159], v[20:23], v[44:47], v[156:159]
	v_mfma_f32_16x16x32_bf16 v[152:155], v[28:31], v[44:47], v[152:155]
	v_mfma_f32_16x16x32_bf16 v[140:143], v[20:23], v[52:55], v[140:143]
	v_mfma_f32_16x16x32_bf16 v[136:139], v[28:31], v[52:55], v[136:139]
	v_mfma_f32_16x16x32_bf16 v[124:127], v[20:23], v[190:193], v[124:127]
	v_mfma_f32_16x16x32_bf16 v[120:123], v[28:31], v[190:193], v[120:123]
	v_mfma_f32_16x16x32_bf16 v[108:111], v[20:23], v[198:201], v[108:111]
	v_mfma_f32_16x16x32_bf16 v[104:107], v[28:31], v[198:201], v[104:107]
	s_setprio 0
	s_barrier
	s_add_i32 s35, s1, s33
	v_lshl_add_u64 v[218:219], s[6:7], 0, v[166:167]
	s_mov_b32 m0, s35
	ds_read_b128 v[202:205], v235
	ds_read_b128 v[206:209], v235 offset:1024
	ds_read_b128 v[210:213], v235 offset:2048
	ds_read_b128 v[214:217], v235 offset:3072
	global_load_lds_dwordx4 v[218:219], off
	v_lshl_add_u64 v[246:247], s[6:7], 0, v[162:163]
	s_add_i32 m0, s35, 0x2000
	s_nop 0
	global_load_lds_dwordx4 v[246:247], off
	s_barrier
	s_waitcnt lgkmcnt(0)
	s_setprio 1
	s_waitcnt lgkmcnt(0)
	v_mfma_f32_16x16x32_bf16 v[148:151], v[202:205], v[40:43], v[148:151]
	v_mfma_f32_16x16x32_bf16 v[40:43], v[210:213], v[40:43], v[144:147]
	v_mfma_f32_16x16x32_bf16 v[148:151], v[206:209], v[44:47], v[148:151]
	v_mfma_f32_16x16x32_bf16 v[40:43], v[214:217], v[44:47], v[40:43]
	v_mfma_f32_16x16x32_bf16 v[44:47], v[202:205], v[48:51], v[132:135]
	v_mfma_f32_16x16x32_bf16 v[48:51], v[210:213], v[48:51], v[128:131]
	v_mfma_f32_16x16x32_bf16 v[112:115], v[210:213], v[186:189], v[112:115]
	v_mfma_f32_16x16x32_bf16 v[100:103], v[202:205], v[194:197], v[100:103]
	v_mfma_f32_16x16x32_bf16 v[96:99], v[210:213], v[194:197], v[96:99]
	v_mfma_f32_16x16x32_bf16 v[44:47], v[206:209], v[52:55], v[44:47]
	v_mfma_f32_16x16x32_bf16 v[48:51], v[214:217], v[52:55], v[48:51]
	v_mfma_f32_16x16x32_bf16 v[52:55], v[202:205], v[186:189], v[116:119]
	v_mfma_f32_16x16x32_bf16 v[112:115], v[214:217], v[190:193], v[112:115]
	v_mfma_f32_16x16x32_bf16 v[100:103], v[206:209], v[198:201], v[100:103]
	v_mfma_f32_16x16x32_bf16 v[96:99], v[214:217], v[198:201], v[96:99]
	v_mfma_f32_16x16x32_bf16 v[52:55], v[206:209], v[190:193], v[52:55]
	s_setprio 0
	s_mov_b32 m0, s92
	v_lshl_add_u64 v[248:249], s[8:9], 0, v[168:169]
	s_barrier
	ds_read_b128 v[116:119], v234 offset:16384
	ds_read_b128 v[128:131], v234 offset:17408
	ds_read_b128 v[132:135], v234 offset:18432
	ds_read_b128 v[144:147], v234 offset:19456
	ds_read_b128 v[186:189], v234 offset:20480
	ds_read_b128 v[190:193], v234 offset:21504
	ds_read_b128 v[194:197], v234 offset:22528
	ds_read_b128 v[198:201], v234 offset:23552
	global_load_lds_dwordx4 v[248:249], off
	v_lshl_add_u64 v[250:251], s[8:9], 0, v[164:165]
	s_mov_b32 m0, s93
	s_nop 0
	global_load_lds_dwordx4 v[250:251], off
	s_barrier
	s_waitcnt lgkmcnt(0)
	s_setprio 1
	s_waitcnt lgkmcnt(0)
	v_mfma_f32_16x16x32_bf16 v[92:95], v[16:19], v[116:119], v[92:95]
	v_mfma_f32_16x16x32_bf16 v[88:91], v[24:27], v[116:119], v[88:91]
	v_mfma_f32_16x16x32_bf16 v[76:79], v[16:19], v[132:135], v[76:79]
	v_mfma_f32_16x16x32_bf16 v[72:75], v[24:27], v[132:135], v[72:75]
	v_mfma_f32_16x16x32_bf16 v[60:63], v[16:19], v[186:189], v[60:63]
	v_mfma_f32_16x16x32_bf16 v[56:59], v[24:27], v[186:189], v[56:59]
	v_mfma_f32_16x16x32_bf16 v[12:15], v[16:19], v[194:197], v[12:15]
	v_mfma_f32_16x16x32_bf16 v[8:11], v[24:27], v[194:197], v[8:11]
	v_mfma_f32_16x16x32_bf16 v[92:95], v[20:23], v[128:131], v[92:95]
	v_mfma_f32_16x16x32_bf16 v[88:91], v[28:31], v[128:131], v[88:91]
	v_mfma_f32_16x16x32_bf16 v[76:79], v[20:23], v[144:147], v[76:79]
	v_mfma_f32_16x16x32_bf16 v[72:75], v[28:31], v[144:147], v[72:75]
	v_mfma_f32_16x16x32_bf16 v[60:63], v[20:23], v[190:193], v[60:63]
	v_mfma_f32_16x16x32_bf16 v[56:59], v[28:31], v[190:193], v[56:59]
	v_mfma_f32_16x16x32_bf16 v[12:15], v[20:23], v[198:201], v[12:15]
	v_mfma_f32_16x16x32_bf16 v[8:11], v[28:31], v[198:201], v[8:11]
	s_setprio 0
	s_barrier
	s_add_u32 s56, s6, 0x40000
	s_addc_u32 s57, s7, 0
	s_add_i32 s35, s18, s33
	v_lshl_add_u64 v[16:17], s[56:57], 0, v[166:167]
	s_mov_b32 m0, s35
	s_nop 0
	global_load_lds_dwordx4 v[16:17], off
	v_lshl_add_u64 v[16:17], s[56:57], 0, v[162:163]
	s_add_i32 m0, s35, 0x2000
	s_nop 0
	global_load_lds_dwordx4 v[16:17], off
	s_waitcnt vmcnt(6)
	s_barrier
	s_setprio 1
	v_mfma_f32_16x16x32_bf16 v[36:39], v[202:205], v[186:189], v[36:39]
	v_mfma_f32_16x16x32_bf16 v[32:35], v[210:213], v[186:189], v[32:35]
	v_mfma_f32_16x16x32_bf16 v[4:7], v[202:205], v[194:197], v[4:7]
	v_mfma_f32_16x16x32_bf16 v[0:3], v[210:213], v[194:197], v[0:3]
	v_mfma_f32_16x16x32_bf16 v[16:19], v[202:205], v[116:119], v[84:87]
	v_mfma_f32_16x16x32_bf16 v[20:23], v[210:213], v[116:119], v[80:83]
	v_mfma_f32_16x16x32_bf16 v[24:27], v[202:205], v[132:135], v[68:71]
	v_mfma_f32_16x16x32_bf16 v[28:31], v[210:213], v[132:135], v[64:67]
	v_mfma_f32_16x16x32_bf16 v[36:39], v[206:209], v[190:193], v[36:39]
	v_mfma_f32_16x16x32_bf16 v[32:35], v[214:217], v[190:193], v[32:35]
	v_mfma_f32_16x16x32_bf16 v[4:7], v[206:209], v[198:201], v[4:7]
	v_mfma_f32_16x16x32_bf16 v[0:3], v[214:217], v[198:201], v[0:3]
	v_mfma_f32_16x16x32_bf16 v[16:19], v[206:209], v[128:131], v[16:19]
	v_mfma_f32_16x16x32_bf16 v[20:23], v[214:217], v[128:131], v[20:23]
	v_mfma_f32_16x16x32_bf16 v[24:27], v[206:209], v[144:147], v[24:27]
	v_mfma_f32_16x16x32_bf16 v[28:31], v[214:217], v[144:147], v[28:31]
	s_setprio 0
	s_add_i32 s35, 0, 0x18000
	v_add_u32_e32 v84, s35, v232
	s_barrier
	ds_read_b128 v[64:67], v84
	ds_read_b128 v[68:71], v84 offset:1024
	ds_read_b128 v[80:83], v84 offset:2048
	ds_read_b128 v[84:87], v84 offset:3072
	s_add_u32 s8, s8, 0x40000
	s_addc_u32 s9, s9, 0
	s_mov_b32 m0, s96
	v_lshl_add_u64 v[132:133], s[8:9], 0, v[168:169]
	ds_read_b128 v[116:119], v234 offset:32768
	ds_read_b128 v[128:131], v234 offset:33792
	ds_read_b128 v[186:189], v234 offset:34816
	ds_read_b128 v[190:193], v234 offset:35840
	ds_read_b128 v[194:197], v234 offset:36864
	ds_read_b128 v[198:201], v234 offset:37888
	ds_read_b128 v[202:205], v234 offset:38912
	ds_read_b128 v[206:209], v234 offset:39936
	global_load_lds_dwordx4 v[132:133], off
	v_lshl_add_u64 v[132:133], s[8:9], 0, v[164:165]
	s_mov_b32 m0, s97
	s_nop 0
	global_load_lds_dwordx4 v[132:133], off
	s_waitcnt lgkmcnt(8)
	s_barrier
	s_waitcnt lgkmcnt(0)
	s_setprio 1
	s_waitcnt lgkmcnt(0)
	v_mfma_f32_16x16x32_bf16 v[132:135], v[64:67], v[116:119], v[156:159]
	v_mfma_f32_16x16x32_bf16 v[156:159], v[68:71], v[128:131], v[132:135]
	v_mfma_f32_16x16x32_bf16 v[132:135], v[80:83], v[116:119], v[152:155]
	v_mfma_f32_16x16x32_bf16 v[152:155], v[84:87], v[128:131], v[132:135]
	v_mfma_f32_16x16x32_bf16 v[132:135], v[64:67], v[186:189], v[140:143]
	v_mfma_f32_16x16x32_bf16 v[140:143], v[68:71], v[190:193], v[132:135]
	v_mfma_f32_16x16x32_bf16 v[132:135], v[80:83], v[186:189], v[136:139]
	v_mfma_f32_16x16x32_bf16 v[124:127], v[64:67], v[194:197], v[124:127]
	v_mfma_f32_16x16x32_bf16 v[120:123], v[80:83], v[194:197], v[120:123]
	v_mfma_f32_16x16x32_bf16 v[108:111], v[64:67], v[202:205], v[108:111]
	v_mfma_f32_16x16x32_bf16 v[104:107], v[80:83], v[202:205], v[104:107]
	v_mfma_f32_16x16x32_bf16 v[136:139], v[84:87], v[190:193], v[132:135]
	v_mfma_f32_16x16x32_bf16 v[124:127], v[68:71], v[198:201], v[124:127]
	v_mfma_f32_16x16x32_bf16 v[120:123], v[84:87], v[198:201], v[120:123]
	v_mfma_f32_16x16x32_bf16 v[108:111], v[68:71], v[206:209], v[108:111]
	v_mfma_f32_16x16x32_bf16 v[104:107], v[84:87], v[206:209], v[104:107]
	s_setprio 0
	s_barrier
	s_add_i32 s8, 0, 0x1c000
	v_add_u32_e32 v132, s8, v232
	s_add_i32 s9, s35, s33
	ds_read_b128 v[210:213], v132
	ds_read_b128 v[214:217], v132 offset:1024
	ds_read_b128 v[238:241], v132 offset:2048
	ds_read_b128 v[242:245], v132 offset:3072
	v_lshl_add_u64 v[132:133], v[218:219], 0, s[14:15]
	s_mov_b32 m0, s9
	s_nop 0
	global_load_lds_dwordx4 v[132:133], off
	v_lshl_add_u64 v[132:133], v[246:247], 0, s[14:15]
	s_add_i32 m0, s9, 0x2000
	s_nop 0
	global_load_lds_dwordx4 v[132:133], off
	s_barrier
	s_waitcnt lgkmcnt(0)
	s_setprio 1
	s_waitcnt lgkmcnt(0)
	v_mfma_f32_16x16x32_bf16 v[40:43], v[238:241], v[116:119], v[40:43]
	v_mfma_f32_16x16x32_bf16 v[132:135], v[210:213], v[116:119], v[148:151]
	v_mfma_f32_16x16x32_bf16 v[144:147], v[242:245], v[128:131], v[40:43]
	v_mfma_f32_16x16x32_bf16 v[40:43], v[210:213], v[186:189], v[44:47]
	v_mfma_f32_16x16x32_bf16 v[148:151], v[214:217], v[128:131], v[132:135]
	v_mfma_f32_16x16x32_bf16 v[132:135], v[214:217], v[190:193], v[40:43]
	v_mfma_f32_16x16x32_bf16 v[40:43], v[238:241], v[186:189], v[48:51]
	v_mfma_f32_16x16x32_bf16 v[128:131], v[242:245], v[190:193], v[40:43]
	v_mfma_f32_16x16x32_bf16 v[40:43], v[210:213], v[194:197], v[52:55]
	v_mfma_f32_16x16x32_bf16 v[116:119], v[214:217], v[198:201], v[40:43]
	v_mfma_f32_16x16x32_bf16 v[40:43], v[238:241], v[194:197], v[112:115]
	v_mfma_f32_16x16x32_bf16 v[112:115], v[242:245], v[198:201], v[40:43]
	v_mfma_f32_16x16x32_bf16 v[40:43], v[210:213], v[202:205], v[100:103]
	v_mfma_f32_16x16x32_bf16 v[100:103], v[214:217], v[206:209], v[40:43]
	v_mfma_f32_16x16x32_bf16 v[40:43], v[238:241], v[202:205], v[96:99]
	v_mfma_f32_16x16x32_bf16 v[96:99], v[242:245], v[206:209], v[40:43]
	s_setprio 0
	s_mov_b32 m0, s53
	v_lshl_add_u64 v[202:203], v[248:249], 0, s[14:15]
	s_barrier
	s_nop 2
	ds_read_b128 v[40:43], v234 offset:49152
	ds_read_b128 v[44:47], v234 offset:50176
	ds_read_b128 v[48:51], v234 offset:51200
	ds_read_b128 v[52:55], v234 offset:52224
	ds_read_b128 v[186:189], v234 offset:53248
	ds_read_b128 v[190:193], v234 offset:54272
	ds_read_b128 v[194:197], v234 offset:55296
	ds_read_b128 v[198:201], v234 offset:56320
	global_load_lds_dwordx4 v[202:203], off
	v_lshl_add_u64 v[202:203], v[250:251], 0, s[14:15]
	s_mov_b32 m0, s23
	s_nop 0
	global_load_lds_dwordx4 v[202:203], off
	s_barrier
	s_waitcnt lgkmcnt(0)
	s_setprio 1
	s_waitcnt lgkmcnt(0)
	v_mfma_f32_16x16x32_bf16 v[92:95], v[64:67], v[40:43], v[92:95]
	v_mfma_f32_16x16x32_bf16 v[88:91], v[80:83], v[40:43], v[88:91]
	v_mfma_f32_16x16x32_bf16 v[76:79], v[64:67], v[48:51], v[76:79]
	v_mfma_f32_16x16x32_bf16 v[72:75], v[80:83], v[48:51], v[72:75]
	v_mfma_f32_16x16x32_bf16 v[60:63], v[64:67], v[186:189], v[60:63]
	v_mfma_f32_16x16x32_bf16 v[56:59], v[80:83], v[186:189], v[56:59]
	v_mfma_f32_16x16x32_bf16 v[12:15], v[64:67], v[194:197], v[12:15]
	v_mfma_f32_16x16x32_bf16 v[8:11], v[80:83], v[194:197], v[8:11]
	v_mfma_f32_16x16x32_bf16 v[92:95], v[68:71], v[44:47], v[92:95]
	v_mfma_f32_16x16x32_bf16 v[88:91], v[84:87], v[44:47], v[88:91]
	v_mfma_f32_16x16x32_bf16 v[76:79], v[68:71], v[52:55], v[76:79]
	v_mfma_f32_16x16x32_bf16 v[72:75], v[84:87], v[52:55], v[72:75]
	v_mfma_f32_16x16x32_bf16 v[60:63], v[68:71], v[190:193], v[60:63]
	v_mfma_f32_16x16x32_bf16 v[56:59], v[84:87], v[190:193], v[56:59]
	v_mfma_f32_16x16x32_bf16 v[12:15], v[68:71], v[198:201], v[12:15]
	v_mfma_f32_16x16x32_bf16 v[8:11], v[84:87], v[198:201], v[8:11]
	s_setprio 0
	s_barrier
	s_add_u32 s6, s6, 0x40080
	s_addc_u32 s7, s7, 0
	s_add_i32 s8, s8, s33
	v_lshl_add_u64 v[64:65], s[6:7], 0, v[166:167]
	s_mov_b32 m0, s8
	s_nop 0
	global_load_lds_dwordx4 v[64:65], off
	v_lshl_add_u64 v[64:65], s[6:7], 0, v[162:163]
	s_add_i32 m0, s8, 0x2000
	s_nop 0
	global_load_lds_dwordx4 v[64:65], off
	s_waitcnt vmcnt(6)
	s_barrier
	s_setprio 1
	v_mfma_f32_16x16x32_bf16 v[16:19], v[210:213], v[40:43], v[16:19]
	v_mfma_f32_16x16x32_bf16 v[84:87], v[214:217], v[44:47], v[16:19]
	v_mfma_f32_16x16x32_bf16 v[16:19], v[238:241], v[40:43], v[20:23]
	v_mfma_f32_16x16x32_bf16 v[80:83], v[242:245], v[44:47], v[16:19]
	v_mfma_f32_16x16x32_bf16 v[16:19], v[210:213], v[48:51], v[24:27]
	v_mfma_f32_16x16x32_bf16 v[68:71], v[214:217], v[52:55], v[16:19]
	v_mfma_f32_16x16x32_bf16 v[16:19], v[238:241], v[48:51], v[28:31]
	v_mfma_f32_16x16x32_bf16 v[64:67], v[242:245], v[52:55], v[16:19]
	v_mfma_f32_16x16x32_bf16 v[16:19], v[210:213], v[186:189], v[36:39]
	v_mfma_f32_16x16x32_bf16 v[36:39], v[214:217], v[190:193], v[16:19]
	v_mfma_f32_16x16x32_bf16 v[16:19], v[238:241], v[186:189], v[32:35]
	v_mfma_f32_16x16x32_bf16 v[4:7], v[210:213], v[194:197], v[4:7]
	v_mfma_f32_16x16x32_bf16 v[0:3], v[238:241], v[194:197], v[0:3]
	v_mfma_f32_16x16x32_bf16 v[32:35], v[242:245], v[190:193], v[16:19]
	v_mfma_f32_16x16x32_bf16 v[4:7], v[214:217], v[198:201], v[4:7]
	v_mfma_f32_16x16x32_bf16 v[0:3], v[242:245], v[198:201], v[0:3]
	s_setprio 0
	s_add_i32 s34, s34, 2
	s_add_u32 s4, s4, 0x100
	s_addc_u32 s5, s5, 0
	s_add_u32 s30, s30, 0x100
	s_addc_u32 s31, s31, 0
	s_cmp_gt_u32 s34, 13
	s_barrier
	s_cbranch_scc0 .LBB0_175
	s_cmp_gt_i32 s28, 1
	s_cselect_b64 s[6:7], -1, 0
	s_cmp_lt_i32 s28, 2
	s_cselect_b64 s[4:5], -1, 0
	s_add_i32 s8, s28, -3
	s_cmp_lt_u32 s8, 2
	s_cselect_b64 s[8:9], -1, 0
	s_lshl_b32 s29, s12, 8
	s_add_i32 s29, s29, s52
	v_or_b32_e32 v196, s29, v179
	v_readlane_b32 s64, v253, 55
	v_ashrrev_i32_e32 v197, 31, v196
	v_readlane_b32 s72, v253, 63
	v_readlane_b32 s73, v252, 0
	s_or_b64 s[4:5], s[4:5], s[8:9]
	s_and_b32 s8, s29, 0xfc0
	v_lshl_add_u64 v[16:17], v[196:197], 2, s[72:73]
	global_load_dword v204, v[16:17], off
	global_load_dword v200, v[16:17], off offset:64
	global_load_dword v198, v[16:17], off offset:128
	global_load_dword v194, v[16:17], off offset:192
	global_load_dword v192, v[16:17], off offset:512
	global_load_dword v190, v[16:17], off offset:576
	global_load_dword v188, v[16:17], off offset:640
	global_load_dword v186, v[16:17], off offset:704
	v_or_b32_e32 v16, s8, v179
	v_readlane_b32 s8, v252, 45
	v_readlane_b32 s9, v252, 46
	s_and_b64 s[62:63], s[8:9], s[4:5]
	v_cndmask_b32_e64 v17, 0, 1, s[62:63]
	v_readlane_b32 s68, v253, 59
	v_readlane_b32 s69, v253, 60
	v_readlane_b32 s76, v252, 3
	v_readlane_b32 s77, v252, 4
	v_readlane_b32 s78, v252, 5
	v_readlane_b32 s79, v252, 6
	v_cmp_ne_u32_e64 s[4:5], 1, v17
	s_andn2_b64 vcc, exec, s[62:63]
	v_lshlrev_b32_e32 v187, 6, v16
	v_readlane_b32 s65, v253, 56
	v_readlane_b32 s66, v253, 57
	v_readlane_b32 s67, v253, 58
	v_readlane_b32 s70, v253, 61
	v_readlane_b32 s71, v253, 62
	v_readlane_b32 s74, v252, 1
	v_readlane_b32 s75, v252, 2
	s_cbranch_vccnz .LBB0_178
	global_load_dwordx4 v[40:43], v187, s[76:77] offset:48
	global_load_dwordx4 v[44:47], v187, s[76:77] offset:32
	global_load_dwordx4 v[48:51], v187, s[76:77] offset:16
	global_load_dwordx4 v[52:55], v187, s[76:77]
	global_load_dwordx4 v[16:19], v187, s[76:77] offset:1072
	global_load_dwordx4 v[20:23], v187, s[76:77] offset:1056
	global_load_dwordx4 v[24:27], v187, s[76:77] offset:1040
	global_load_dwordx4 v[28:31], v187, s[76:77] offset:1024
